# all neutral edits together: cvt_pk packs, paired load issue in branch-GEMM epilogue (groups 2-7), early FoX K/V DMA, grid-barrier invalidate issued by wave 1 at arrival, followers poll top generation
# speedup vs baseline: 1.0131x; 1.0131x over previous
.LBB9_124:
	s_waitcnt vmcnt(1)
	v_lshlrev_b32_e32 v158, 16, v146
	v_and_b32_e32 v146, 0xffff0000, v146
	v_add_f32_e32 v146, v59, v146
	v_lshlrev_b32_e32 v159, 16, v147
	v_mul_f32_e32 v146, 0xbfb8aa3b, v146
	v_add_f32_e32 v159, v60, v159
	v_exp_f32_e32 v146, v146
	v_mul_f32_e32 v159, 0xbfb8aa3b, v159
	v_exp_f32_e32 v160, v159
	v_and_b32_e32 v147, 0xffff0000, v147
	v_add_f32_e32 v146, 1.0, v146
	v_rcp_f32_e32 v159, v146
	v_add_f32_e32 v146, 1.0, v160
	v_lshlrev_b32_e32 v160, 16, v148
	v_and_b32_e32 v148, 0xffff0000, v148
	v_lshlrev_b32_e32 v161, 16, v149
	v_and_b32_e32 v149, 0xffff0000, v149
	v_add_f32_e32 v158, v58, v158
	v_add_f32_e32 v147, v61, v147
	v_add_f32_e32 v160, v50, v160
	v_add_f32_e32 v148, v51, v148
	v_add_f32_e32 v161, v52, v161
	v_add_f32_e32 v149, v53, v149
	v_mul_f32_e32 v158, 0xbfb8aa3b, v158
	v_mul_f32_e32 v147, 0xbfb8aa3b, v147
	v_mul_f32_e32 v160, 0xbfb8aa3b, v160
	v_mul_f32_e32 v148, 0xbfb8aa3b, v148
	v_mul_f32_e32 v161, 0xbfb8aa3b, v161
	v_mul_f32_e32 v149, 0xbfb8aa3b, v149
	v_exp_f32_e32 v158, v158
	v_exp_f32_e32 v147, v147
	v_exp_f32_e32 v160, v160
	v_exp_f32_e32 v148, v148
	v_exp_f32_e32 v161, v161
	v_exp_f32_e32 v149, v149
	v_add_f32_e32 v158, 1.0, v158
	v_add_f32_e32 v147, 1.0, v147
	v_add_f32_e32 v160, 1.0, v160
	v_add_f32_e32 v162, 1.0, v148
	v_add_f32_e32 v148, 1.0, v161
	v_add_f32_e32 v149, 1.0, v149
	v_rcp_f32_e32 v158, v158
	v_rcp_f32_e32 v146, v146
	v_rcp_f32_e32 v147, v147
	v_rcp_f32_e32 v160, v160
	v_rcp_f32_e32 v148, v148
	v_rcp_f32_e32 v149, v149
	v_rcp_f32_e32 v161, v162
	v_lshl_add_u64 v[156:157], v[156:157], 1, s[50:51]
	v_pk_fma_f32 v[128:129], v[128:129], v[146:147], v[152:153]
	v_pk_fma_f32 v[126:127], v[126:127], v[158:159], v[150:151]
	v_pk_fma_f32 v[124:125], v[124:125], v[148:149], v[144:145]
	v_pk_fma_f32 v[122:123], v[122:123], v[160:161], v[142:143]
	s_and_b64 vcc, exec, s[8:9]
	s_mov_b64 s[28:29], -1
	s_cbranch_vccnz .LBB9_126
	v_cvt_pk_bf16_f32 v142, v126, v127
	v_cvt_pk_bf16_f32 v143, v128, v129
	v_cvt_pk_bf16_f32 v144, v122, v123
	v_cvt_pk_bf16_f32 v145, v124, v125
	s_mov_b64 s[28:29], 0
	global_store_dwordx4 v[156:157], v[142:145], off
.LBB9_126:
	s_andn2_b64 vcc, exec, s[28:29]
	s_cbranch_vccnz .LBB9_128
	global_store_dwordx4 v[154:155], v[126:129], off
	global_store_dwordx4 v[154:155], v[122:125], off offset:16
.LBB9_128:
	s_waitcnt vmcnt(0)
	s_nop 0
	v_lshlrev_b32_e32 v122, 16, v134
	v_and_b32_e32 v123, 0xffff0000, v134
	v_lshlrev_b32_e32 v124, 16, v135
	v_and_b32_e32 v125, 0xffff0000, v135
	v_lshlrev_b32_e32 v126, 16, v136
	v_and_b32_e32 v127, 0xffff0000, v136
	v_lshlrev_b32_e32 v128, 16, v137
	v_and_b32_e32 v129, 0xffff0000, v137
	v_add_f32_e32 v122, v46, v122
	v_add_f32_e32 v123, v47, v123
	v_add_f32_e32 v124, v48, v124
	v_add_f32_e32 v125, v49, v125
	v_add_f32_e32 v126, v42, v126
	v_add_f32_e32 v127, v43, v127
	v_add_f32_e32 v128, v44, v128
	v_add_f32_e32 v129, v45, v129
	v_mul_f32_e32 v122, 0xbfb8aa3b, v122
	v_mul_f32_e32 v123, 0xbfb8aa3b, v123
	v_mul_f32_e32 v124, 0xbfb8aa3b, v124
	v_mul_f32_e32 v125, 0xbfb8aa3b, v125
	v_mul_f32_e32 v126, 0xbfb8aa3b, v126
	v_mul_f32_e32 v127, 0xbfb8aa3b, v127
	v_mul_f32_e32 v128, 0xbfb8aa3b, v128
	v_mul_f32_e32 v129, 0xbfb8aa3b, v129
	v_exp_f32_e32 v122, v122
	v_exp_f32_e32 v123, v123
	v_exp_f32_e32 v124, v124
	v_exp_f32_e32 v125, v125
	v_exp_f32_e32 v126, v126
	v_exp_f32_e32 v127, v127
	v_exp_f32_e32 v128, v128
	v_exp_f32_e32 v129, v129
	v_add_f32_e32 v122, 1.0, v122
	v_add_f32_e32 v123, 1.0, v123
	v_add_f32_e32 v124, 1.0, v124
	v_add_f32_e32 v125, 1.0, v125
	v_add_f32_e32 v126, 1.0, v126
	v_add_f32_e32 v127, 1.0, v127
	v_add_f32_e32 v128, 1.0, v128
	v_add_f32_e32 v129, 1.0, v129
	v_rcp_f32_e32 v122, v122
	v_rcp_f32_e32 v123, v123
	v_rcp_f32_e32 v124, v124
	v_rcp_f32_e32 v125, v125
	v_rcp_f32_e32 v126, v126
	v_rcp_f32_e32 v128, v128
	v_rcp_f32_e32 v129, v129
	v_rcp_f32_e32 v127, v127
	v_pk_fma_f32 v[120:121], v[120:121], v[124:125], v[140:141]
	v_pk_fma_f32 v[118:119], v[118:119], v[122:123], v[138:139]
	v_pk_fma_f32 v[116:117], v[116:117], v[128:129], v[132:133]
	v_pk_fma_f32 v[114:115], v[114:115], v[126:127], v[130:131]
	s_and_b64 vcc, exec, s[8:9]
	s_mov_b64 s[28:29], -1
	s_cbranch_vccnz .LBB9_130
	v_cvt_pk_bf16_f32 v122, v118, v119
	v_cvt_pk_bf16_f32 v123, v120, v121
	v_cvt_pk_bf16_f32 v124, v114, v115
	v_cvt_pk_bf16_f32 v125, v116, v117
	s_mov_b64 s[28:29], 0
	global_store_dwordx4 v[156:157], v[122:125], off offset:256

.LBB9_140:
	s_nop 1
	v_add_u32_e32 v150, 48, v184
	v_ashrrev_i32_e32 v151, 31, v150
	v_lshlrev_b64 v[148:149], 13, v[150:151]
	v_lshl_add_u64 v[148:149], v[180:181], 0, v[148:149]
	global_load_dwordx4 v[164:167], v[148:149], off
	s_and_b64 vcc, exec, s[6:7]
	s_mov_b64 s[28:29], -1
	s_cbranch_vccnz .LBB9_150
	s_mov_b64 s[28:29], 0
.LBB9_150:
	v_lshlrev_b64 v[150:151], 10, v[150:151]
	v_lshl_add_u64 v[194:195], v[150:151], 0, v[182:183]
	v_lshl_add_u64 v[168:169], v[194:195], 2, s[18:19]
	v_mov_b32_e32 v160, 0
	s_andn2_b64 vcc, exec, s[28:29]
	v_mov_b32_e32 v161, 0
	v_mov_b32_e32 v162, 0
	v_mov_b32_e32 v163, 0
	v_mov_b32_e32 v186, 0
	v_mov_b32_e32 v187, 0
	v_mov_b32_e32 v188, 0
	v_mov_b32_e32 v189, 0
	s_cbranch_vccnz .LBB9_152
	global_load_dwordx4 v[160:163], v[168:169], off offset:16
	global_load_dwordx4 v[186:189], v[168:169], off
.LBB9_152:
	global_load_dwordx4 v[152:155], v[148:149], off offset:256
	s_and_b64 vcc, exec, s[6:7]
	s_mov_b64 s[28:29], -1
	s_cbranch_vccnz .LBB9_154
	s_mov_b64 s[28:29], 0
.LBB9_154:
	v_mov_b32_e32 v148, 0
	s_andn2_b64 vcc, exec, s[28:29]
	v_mov_b32_e32 v149, 0
	v_mov_b32_e32 v150, 0
	v_mov_b32_e32 v151, 0
	v_mov_b32_e32 v156, 0
	v_mov_b32_e32 v157, 0
	v_mov_b32_e32 v158, 0
	v_mov_b32_e32 v159, 0
	s_cbranch_vccnz .LBB9_156
	global_load_dwordx4 v[148:151], v[168:169], off offset:528
	global_load_dwordx4 v[156:159], v[168:169], off offset:512
.LBB9_156:
	s_waitcnt vmcnt(1)
	v_lshlrev_b32_e32 v142, 16, v130
	v_and_b32_e32 v130, 0xffff0000, v130
	v_add_f32_e32 v130, v59, v130
	v_lshlrev_b32_e32 v143, 16, v131
	v_mul_f32_e32 v130, 0xbfb8aa3b, v130
	v_add_f32_e32 v143, v60, v143
	v_exp_f32_e32 v130, v130
	v_mul_f32_e32 v143, 0xbfb8aa3b, v143
	v_exp_f32_e32 v144, v143
	v_and_b32_e32 v131, 0xffff0000, v131
	v_add_f32_e32 v130, 1.0, v130
	v_rcp_f32_e32 v143, v130
	v_add_f32_e32 v130, 1.0, v144
	v_lshlrev_b32_e32 v144, 16, v132
	v_and_b32_e32 v132, 0xffff0000, v132
	v_lshlrev_b32_e32 v145, 16, v133
	v_and_b32_e32 v133, 0xffff0000, v133
	v_add_f32_e32 v142, v58, v142
	v_add_f32_e32 v131, v61, v131
	v_add_f32_e32 v144, v50, v144
	v_add_f32_e32 v132, v51, v132
	v_add_f32_e32 v145, v52, v145
	v_add_f32_e32 v133, v53, v133
	v_mul_f32_e32 v142, 0xbfb8aa3b, v142
	v_mul_f32_e32 v131, 0xbfb8aa3b, v131
	v_mul_f32_e32 v144, 0xbfb8aa3b, v144
	v_mul_f32_e32 v132, 0xbfb8aa3b, v132
	v_mul_f32_e32 v145, 0xbfb8aa3b, v145
	v_mul_f32_e32 v133, 0xbfb8aa3b, v133
	v_exp_f32_e32 v142, v142
	v_exp_f32_e32 v131, v131
	v_exp_f32_e32 v144, v144
	v_exp_f32_e32 v132, v132
	v_exp_f32_e32 v145, v145
	v_exp_f32_e32 v133, v133
	v_add_f32_e32 v142, 1.0, v142
	v_add_f32_e32 v131, 1.0, v131
	v_add_f32_e32 v144, 1.0, v144
	v_add_f32_e32 v146, 1.0, v132
	v_add_f32_e32 v132, 1.0, v145
	v_add_f32_e32 v133, 1.0, v133
	v_rcp_f32_e32 v142, v142
	v_rcp_f32_e32 v130, v130
	v_rcp_f32_e32 v131, v131
	v_rcp_f32_e32 v144, v144
	v_rcp_f32_e32 v132, v132
	v_rcp_f32_e32 v133, v133
	v_rcp_f32_e32 v145, v146
	v_lshl_add_u64 v[140:141], v[140:141], 1, s[50:51]
	v_pk_fma_f32 v[112:113], v[112:113], v[130:131], v[136:137]
	v_pk_fma_f32 v[110:111], v[110:111], v[142:143], v[134:135]
	v_pk_fma_f32 v[108:109], v[108:109], v[132:133], v[128:129]
	v_pk_fma_f32 v[106:107], v[106:107], v[144:145], v[126:127]
	s_and_b64 vcc, exec, s[8:9]
	s_mov_b64 s[28:29], -1
	s_cbranch_vccnz .LBB9_142
	v_cvt_pk_bf16_f32 v126, v110, v111
	v_cvt_pk_bf16_f32 v127, v112, v113
	v_cvt_pk_bf16_f32 v128, v106, v107
	v_cvt_pk_bf16_f32 v129, v108, v109
	s_mov_b64 s[28:29], 0
	global_store_dwordx4 v[140:141], v[126:129], off
.LBB9_142:
	s_andn2_b64 vcc, exec, s[28:29]
	s_cbranch_vccnz .LBB9_144
	global_store_dwordx4 v[138:139], v[110:113], off
	global_store_dwordx4 v[138:139], v[106:109], off offset:16
.LBB9_144:
	s_waitcnt vmcnt(0)
	s_nop 0
	v_lshlrev_b32_e32 v106, 16, v118
	v_and_b32_e32 v107, 0xffff0000, v118
	v_lshlrev_b32_e32 v108, 16, v119
	v_and_b32_e32 v109, 0xffff0000, v119
	v_lshlrev_b32_e32 v110, 16, v120
	v_and_b32_e32 v111, 0xffff0000, v120
	v_lshlrev_b32_e32 v112, 16, v121
	v_and_b32_e32 v113, 0xffff0000, v121
	v_add_f32_e32 v106, v46, v106
	v_add_f32_e32 v107, v47, v107
	v_add_f32_e32 v108, v48, v108
	v_add_f32_e32 v109, v49, v109
	v_add_f32_e32 v110, v42, v110
	v_add_f32_e32 v111, v43, v111
	v_add_f32_e32 v112, v44, v112
	v_add_f32_e32 v113, v45, v113
	v_mul_f32_e32 v106, 0xbfb8aa3b, v106
	v_mul_f32_e32 v107, 0xbfb8aa3b, v107
	v_mul_f32_e32 v108, 0xbfb8aa3b, v108
	v_mul_f32_e32 v109, 0xbfb8aa3b, v109
	v_mul_f32_e32 v110, 0xbfb8aa3b, v110
	v_mul_f32_e32 v111, 0xbfb8aa3b, v111
	v_mul_f32_e32 v112, 0xbfb8aa3b, v112
	v_mul_f32_e32 v113, 0xbfb8aa3b, v113
	v_exp_f32_e32 v106, v106
	v_exp_f32_e32 v107, v107
	v_exp_f32_e32 v108, v108
	v_exp_f32_e32 v109, v109
	v_exp_f32_e32 v110, v110
	v_exp_f32_e32 v111, v111
	v_exp_f32_e32 v112, v112
	v_exp_f32_e32 v113, v113
	v_add_f32_e32 v106, 1.0, v106
	v_add_f32_e32 v107, 1.0, v107
	v_add_f32_e32 v108, 1.0, v108
	v_add_f32_e32 v109, 1.0, v109
	v_add_f32_e32 v110, 1.0, v110
	v_add_f32_e32 v111, 1.0, v111
	v_add_f32_e32 v112, 1.0, v112
	v_add_f32_e32 v113, 1.0, v113
	v_rcp_f32_e32 v106, v106
	v_rcp_f32_e32 v107, v107
	v_rcp_f32_e32 v108, v108
	v_rcp_f32_e32 v109, v109
	v_rcp_f32_e32 v110, v110
	v_rcp_f32_e32 v112, v112
	v_rcp_f32_e32 v113, v113
	v_rcp_f32_e32 v111, v111
	v_pk_fma_f32 v[104:105], v[104:105], v[108:109], v[124:125]
	v_pk_fma_f32 v[102:103], v[102:103], v[106:107], v[122:123]
	v_pk_fma_f32 v[100:101], v[100:101], v[112:113], v[116:117]
	v_pk_fma_f32 v[98:99], v[98:99], v[110:111], v[114:115]
	s_and_b64 vcc, exec, s[8:9]
	s_mov_b64 s[28:29], -1
	s_cbranch_vccnz .LBB9_146
	v_cvt_pk_bf16_f32 v106, v102, v103
	v_cvt_pk_bf16_f32 v107, v104, v105
	v_cvt_pk_bf16_f32 v108, v98, v99
	v_cvt_pk_bf16_f32 v109, v100, v101
	s_mov_b64 s[28:29], 0
	global_store_dwordx4 v[140:141], v[106:109], off offset:256

.LBB9_148:
	s_waitcnt vmcnt(1)
	v_lshlrev_b32_e32 v126, 16, v164
	v_and_b32_e32 v164, 0xffff0000, v164
	v_add_f32_e32 v164, v59, v164
	v_lshlrev_b32_e32 v127, 16, v165
	v_mul_f32_e32 v164, 0xbfb8aa3b, v164
	v_add_f32_e32 v127, v60, v127
	v_exp_f32_e32 v164, v164
	v_mul_f32_e32 v127, 0xbfb8aa3b, v127
	v_exp_f32_e32 v128, v127
	v_and_b32_e32 v165, 0xffff0000, v165
	v_add_f32_e32 v164, 1.0, v164
	v_rcp_f32_e32 v127, v164
	v_add_f32_e32 v164, 1.0, v128
	v_lshlrev_b32_e32 v128, 16, v166
	v_and_b32_e32 v166, 0xffff0000, v166
	v_lshlrev_b32_e32 v129, 16, v167
	v_and_b32_e32 v167, 0xffff0000, v167
	v_add_f32_e32 v126, v58, v126
	v_add_f32_e32 v165, v61, v165
	v_add_f32_e32 v128, v50, v128
	v_add_f32_e32 v166, v51, v166
	v_add_f32_e32 v129, v52, v129
	v_add_f32_e32 v167, v53, v167
	v_mul_f32_e32 v126, 0xbfb8aa3b, v126
	v_mul_f32_e32 v165, 0xbfb8aa3b, v165
	v_mul_f32_e32 v128, 0xbfb8aa3b, v128
	v_mul_f32_e32 v166, 0xbfb8aa3b, v166
	v_mul_f32_e32 v129, 0xbfb8aa3b, v129
	v_mul_f32_e32 v167, 0xbfb8aa3b, v167
	v_exp_f32_e32 v126, v126
	v_exp_f32_e32 v165, v165
	v_exp_f32_e32 v128, v128
	v_exp_f32_e32 v166, v166
	v_exp_f32_e32 v129, v129
	v_exp_f32_e32 v167, v167
	v_add_f32_e32 v126, 1.0, v126
	v_add_f32_e32 v165, 1.0, v165
	v_add_f32_e32 v128, 1.0, v128
	v_add_f32_e32 v130, 1.0, v166
	v_add_f32_e32 v166, 1.0, v129
	v_add_f32_e32 v167, 1.0, v167
	v_rcp_f32_e32 v126, v126
	v_rcp_f32_e32 v164, v164
	v_rcp_f32_e32 v165, v165
	v_rcp_f32_e32 v128, v128
	v_rcp_f32_e32 v166, v166
	v_rcp_f32_e32 v167, v167
	v_rcp_f32_e32 v129, v130
	v_lshl_add_u64 v[194:195], v[194:195], 1, s[50:51]
	v_pk_fma_f32 v[96:97], v[96:97], v[164:165], v[188:189]
	v_pk_fma_f32 v[94:95], v[94:95], v[126:127], v[186:187]
	v_pk_fma_f32 v[92:93], v[92:93], v[166:167], v[162:163]
	v_pk_fma_f32 v[90:91], v[90:91], v[128:129], v[160:161]
	s_and_b64 vcc, exec, s[8:9]
	s_mov_b64 s[28:29], -1
	s_cbranch_vccnz .LBB9_158
	v_cvt_pk_bf16_f32 v160, v94, v95
	v_cvt_pk_bf16_f32 v161, v96, v97
	v_cvt_pk_bf16_f32 v162, v90, v91
	v_cvt_pk_bf16_f32 v163, v92, v93
	s_mov_b64 s[28:29], 0
	global_store_dwordx4 v[194:195], v[160:163], off
.LBB9_158:
	s_andn2_b64 vcc, exec, s[28:29]
	s_cbranch_vccnz .LBB9_160
	global_store_dwordx4 v[168:169], v[94:97], off
	global_store_dwordx4 v[168:169], v[90:93], off offset:16
.LBB9_160:
	s_waitcnt vmcnt(0)
	s_nop 0
	v_lshlrev_b32_e32 v90, 16, v152
	v_and_b32_e32 v91, 0xffff0000, v152
	v_lshlrev_b32_e32 v92, 16, v153
	v_and_b32_e32 v93, 0xffff0000, v153
	v_lshlrev_b32_e32 v94, 16, v154
	v_and_b32_e32 v95, 0xffff0000, v154
	v_lshlrev_b32_e32 v96, 16, v155
	v_and_b32_e32 v97, 0xffff0000, v155
	v_add_f32_e32 v90, v46, v90
	v_add_f32_e32 v91, v47, v91
	v_add_f32_e32 v92, v48, v92
	v_add_f32_e32 v93, v49, v93
	v_add_f32_e32 v94, v42, v94
	v_add_f32_e32 v95, v43, v95
	v_add_f32_e32 v96, v44, v96
	v_add_f32_e32 v97, v45, v97
	v_mul_f32_e32 v90, 0xbfb8aa3b, v90
	v_mul_f32_e32 v91, 0xbfb8aa3b, v91
	v_mul_f32_e32 v92, 0xbfb8aa3b, v92
	v_mul_f32_e32 v93, 0xbfb8aa3b, v93
	v_mul_f32_e32 v94, 0xbfb8aa3b, v94
	v_mul_f32_e32 v95, 0xbfb8aa3b, v95
	v_mul_f32_e32 v96, 0xbfb8aa3b, v96
	v_mul_f32_e32 v97, 0xbfb8aa3b, v97
	v_exp_f32_e32 v90, v90
	v_exp_f32_e32 v91, v91
	v_exp_f32_e32 v92, v92
	v_exp_f32_e32 v93, v93
	v_exp_f32_e32 v94, v94
	v_exp_f32_e32 v95, v95
	v_exp_f32_e32 v96, v96
	v_exp_f32_e32 v97, v97
	v_add_f32_e32 v90, 1.0, v90
	v_add_f32_e32 v91, 1.0, v91
	v_add_f32_e32 v92, 1.0, v92
	v_add_f32_e32 v93, 1.0, v93
	v_add_f32_e32 v94, 1.0, v94
	v_add_f32_e32 v95, 1.0, v95
	v_add_f32_e32 v96, 1.0, v96
	v_add_f32_e32 v97, 1.0, v97
	v_rcp_f32_e32 v90, v90
	v_rcp_f32_e32 v91, v91
	v_rcp_f32_e32 v92, v92
	v_rcp_f32_e32 v93, v93
	v_rcp_f32_e32 v94, v94
	v_rcp_f32_e32 v96, v96
	v_rcp_f32_e32 v97, v97
	v_rcp_f32_e32 v95, v95
	v_pk_fma_f32 v[88:89], v[88:89], v[92:93], v[158:159]
	v_pk_fma_f32 v[86:87], v[86:87], v[90:91], v[156:157]
	v_pk_fma_f32 v[84:85], v[84:85], v[96:97], v[150:151]
	v_pk_fma_f32 v[82:83], v[82:83], v[94:95], v[148:149]
	s_and_b64 vcc, exec, s[8:9]
	s_mov_b64 s[28:29], -1
	s_cbranch_vccnz .LBB9_162
	v_cvt_pk_bf16_f32 v90, v86, v87
	v_cvt_pk_bf16_f32 v91, v88, v89
	v_cvt_pk_bf16_f32 v92, v82, v83
	v_cvt_pk_bf16_f32 v93, v84, v85
	s_mov_b64 s[28:29], 0
	global_store_dwordx4 v[194:195], v[90:93], off offset:256
.LBB9_162:
	s_andn2_b64 vcc, exec, s[28:29]
	s_cbranch_vccnz .LBB9_164
	global_store_dwordx4 v[168:169], v[86:89], off offset:512
	global_store_dwordx4 v[168:169], v[82:85], off offset:528

.LBB9_172:
	s_nop 1
	v_add_u32_e32 v118, 0x90, v184
	v_ashrrev_i32_e32 v119, 31, v118
	v_lshlrev_b64 v[116:117], 13, v[118:119]
	v_lshl_add_u64 v[116:117], v[180:181], 0, v[116:117]
	global_load_dwordx4 v[132:135], v[116:117], off
	s_and_b64 vcc, exec, s[6:7]
	s_mov_b64 s[28:29], -1
	s_cbranch_vccnz .LBB9_182
	s_mov_b64 s[28:29], 0
.LBB9_182:
	v_lshlrev_b64 v[118:119], 10, v[118:119]
	v_lshl_add_u64 v[142:143], v[118:119], 0, v[182:183]
	v_lshl_add_u64 v[140:141], v[142:143], 2, s[18:19]
	v_mov_b32_e32 v128, 0
	s_andn2_b64 vcc, exec, s[28:29]
	v_mov_b32_e32 v129, 0
	v_mov_b32_e32 v130, 0
	v_mov_b32_e32 v131, 0
	v_mov_b32_e32 v136, 0
	v_mov_b32_e32 v137, 0
	v_mov_b32_e32 v138, 0
	v_mov_b32_e32 v139, 0
	s_cbranch_vccnz .LBB9_184
	global_load_dwordx4 v[128:131], v[140:141], off offset:16
	global_load_dwordx4 v[136:139], v[140:141], off
.LBB9_184:
	global_load_dwordx4 v[120:123], v[116:117], off offset:256
	s_and_b64 vcc, exec, s[6:7]
	s_mov_b64 s[28:29], -1
	s_cbranch_vccnz .LBB9_186
	s_mov_b64 s[28:29], 0
.LBB9_186:
	v_mov_b32_e32 v116, 0
	s_andn2_b64 vcc, exec, s[28:29]
	v_mov_b32_e32 v117, 0
	v_mov_b32_e32 v118, 0
	v_mov_b32_e32 v119, 0
	v_mov_b32_e32 v124, 0
	v_mov_b32_e32 v125, 0
	v_mov_b32_e32 v126, 0
	v_mov_b32_e32 v127, 0
	s_cbranch_vccnz .LBB9_188
	global_load_dwordx4 v[116:119], v[140:141], off offset:528
	global_load_dwordx4 v[124:127], v[140:141], off offset:512
.LBB9_188:
	s_waitcnt vmcnt(1)
	v_lshlrev_b32_e32 v110, 16, v98
	v_and_b32_e32 v98, 0xffff0000, v98
	v_add_f32_e32 v98, v59, v98
	v_lshlrev_b32_e32 v111, 16, v99
	v_mul_f32_e32 v98, 0xbfb8aa3b, v98
	v_add_f32_e32 v111, v60, v111
	v_exp_f32_e32 v98, v98
	v_mul_f32_e32 v111, 0xbfb8aa3b, v111
	v_exp_f32_e32 v112, v111
	v_and_b32_e32 v99, 0xffff0000, v99
	v_add_f32_e32 v98, 1.0, v98
	v_rcp_f32_e32 v111, v98
	v_add_f32_e32 v98, 1.0, v112
	v_lshlrev_b32_e32 v112, 16, v100
	v_and_b32_e32 v100, 0xffff0000, v100
	v_lshlrev_b32_e32 v113, 16, v101
	v_and_b32_e32 v101, 0xffff0000, v101
	v_add_f32_e32 v110, v58, v110
	v_add_f32_e32 v99, v61, v99
	v_add_f32_e32 v112, v50, v112
	v_add_f32_e32 v100, v51, v100
	v_add_f32_e32 v113, v52, v113
	v_add_f32_e32 v101, v53, v101
	v_mul_f32_e32 v110, 0xbfb8aa3b, v110
	v_mul_f32_e32 v99, 0xbfb8aa3b, v99
	v_mul_f32_e32 v112, 0xbfb8aa3b, v112
	v_mul_f32_e32 v100, 0xbfb8aa3b, v100
	v_mul_f32_e32 v113, 0xbfb8aa3b, v113
	v_mul_f32_e32 v101, 0xbfb8aa3b, v101
	v_exp_f32_e32 v110, v110
	v_exp_f32_e32 v99, v99
	v_exp_f32_e32 v112, v112
	v_exp_f32_e32 v100, v100
	v_exp_f32_e32 v113, v113
	v_exp_f32_e32 v101, v101
	v_add_f32_e32 v110, 1.0, v110
	v_add_f32_e32 v99, 1.0, v99
	v_add_f32_e32 v112, 1.0, v112
	v_add_f32_e32 v114, 1.0, v100
	v_add_f32_e32 v100, 1.0, v113
	v_add_f32_e32 v101, 1.0, v101
	v_rcp_f32_e32 v110, v110
	v_rcp_f32_e32 v98, v98
	v_rcp_f32_e32 v99, v99
	v_rcp_f32_e32 v112, v112
	v_rcp_f32_e32 v100, v100
	v_rcp_f32_e32 v101, v101
	v_rcp_f32_e32 v113, v114
	v_lshl_add_u64 v[108:109], v[108:109], 1, s[50:51]
	v_pk_fma_f32 v[80:81], v[80:81], v[98:99], v[104:105]
	v_pk_fma_f32 v[78:79], v[78:79], v[110:111], v[102:103]
	v_pk_fma_f32 v[76:77], v[76:77], v[100:101], v[96:97]
	v_pk_fma_f32 v[74:75], v[74:75], v[112:113], v[94:95]
	s_and_b64 vcc, exec, s[8:9]
	s_mov_b64 s[28:29], -1
	s_cbranch_vccnz .LBB9_174
	v_cvt_pk_bf16_f32 v94, v78, v79
	v_cvt_pk_bf16_f32 v95, v80, v81
	v_cvt_pk_bf16_f32 v96, v74, v75
	v_cvt_pk_bf16_f32 v97, v76, v77
	s_mov_b64 s[28:29], 0
	global_store_dwordx4 v[108:109], v[94:97], off
.LBB9_174:
	s_andn2_b64 vcc, exec, s[28:29]
	s_cbranch_vccnz .LBB9_176
	global_store_dwordx4 v[106:107], v[78:81], off
	global_store_dwordx4 v[106:107], v[74:77], off offset:16
.LBB9_176:
	s_waitcnt vmcnt(0)
	s_nop 0
	v_lshlrev_b32_e32 v74, 16, v86
	v_and_b32_e32 v75, 0xffff0000, v86
	v_lshlrev_b32_e32 v76, 16, v87
	v_and_b32_e32 v77, 0xffff0000, v87
	v_lshlrev_b32_e32 v78, 16, v88
	v_and_b32_e32 v79, 0xffff0000, v88
	v_lshlrev_b32_e32 v80, 16, v89
	v_and_b32_e32 v81, 0xffff0000, v89
	v_add_f32_e32 v74, v46, v74
	v_add_f32_e32 v75, v47, v75
	v_add_f32_e32 v76, v48, v76
	v_add_f32_e32 v77, v49, v77
	v_add_f32_e32 v78, v42, v78
	v_add_f32_e32 v79, v43, v79
	v_add_f32_e32 v80, v44, v80
	v_add_f32_e32 v81, v45, v81
	v_mul_f32_e32 v74, 0xbfb8aa3b, v74
	v_mul_f32_e32 v75, 0xbfb8aa3b, v75
	v_mul_f32_e32 v76, 0xbfb8aa3b, v76
	v_mul_f32_e32 v77, 0xbfb8aa3b, v77
	v_mul_f32_e32 v78, 0xbfb8aa3b, v78
	v_mul_f32_e32 v79, 0xbfb8aa3b, v79
	v_mul_f32_e32 v80, 0xbfb8aa3b, v80
	v_mul_f32_e32 v81, 0xbfb8aa3b, v81
	v_exp_f32_e32 v74, v74
	v_exp_f32_e32 v75, v75
	v_exp_f32_e32 v76, v76
	v_exp_f32_e32 v77, v77
	v_exp_f32_e32 v78, v78
	v_exp_f32_e32 v79, v79
	v_exp_f32_e32 v80, v80
	v_exp_f32_e32 v81, v81
	v_add_f32_e32 v74, 1.0, v74
	v_add_f32_e32 v75, 1.0, v75
	v_add_f32_e32 v76, 1.0, v76
	v_add_f32_e32 v77, 1.0, v77
	v_add_f32_e32 v78, 1.0, v78
	v_add_f32_e32 v79, 1.0, v79
	v_add_f32_e32 v80, 1.0, v80
	v_add_f32_e32 v81, 1.0, v81
	v_rcp_f32_e32 v74, v74
	v_rcp_f32_e32 v75, v75
	v_rcp_f32_e32 v76, v76
	v_rcp_f32_e32 v77, v77
	v_rcp_f32_e32 v78, v78
	v_rcp_f32_e32 v80, v80
	v_rcp_f32_e32 v81, v81
	v_rcp_f32_e32 v79, v79
	v_pk_fma_f32 v[72:73], v[72:73], v[76:77], v[92:93]
	v_pk_fma_f32 v[70:71], v[70:71], v[74:75], v[90:91]
	v_pk_fma_f32 v[68:69], v[68:69], v[80:81], v[84:85]
	v_pk_fma_f32 v[66:67], v[66:67], v[78:79], v[82:83]
	s_and_b64 vcc, exec, s[8:9]
	s_mov_b64 s[28:29], -1
	s_cbranch_vccnz .LBB9_178
	v_cvt_pk_bf16_f32 v74, v70, v71
	v_cvt_pk_bf16_f32 v75, v72, v73
	v_cvt_pk_bf16_f32 v76, v66, v67
	v_cvt_pk_bf16_f32 v77, v68, v69
	s_mov_b64 s[28:29], 0
	global_store_dwordx4 v[108:109], v[74:77], off offset:256

.LBB9_180:
	s_waitcnt vmcnt(1)
	v_lshlrev_b32_e32 v94, 16, v132
	v_and_b32_e32 v132, 0xffff0000, v132
	v_add_f32_e32 v132, v59, v132
	v_lshlrev_b32_e32 v95, 16, v133
	v_mul_f32_e32 v132, 0xbfb8aa3b, v132
	v_add_f32_e32 v95, v60, v95
	v_exp_f32_e32 v132, v132
	v_mul_f32_e32 v95, 0xbfb8aa3b, v95
	v_exp_f32_e32 v96, v95
	v_and_b32_e32 v133, 0xffff0000, v133
	v_add_f32_e32 v132, 1.0, v132
	v_rcp_f32_e32 v95, v132
	v_add_f32_e32 v132, 1.0, v96
	v_lshlrev_b32_e32 v96, 16, v134
	v_and_b32_e32 v134, 0xffff0000, v134
	v_lshlrev_b32_e32 v97, 16, v135
	v_and_b32_e32 v135, 0xffff0000, v135
	v_add_f32_e32 v94, v58, v94
	v_add_f32_e32 v133, v61, v133
	v_add_f32_e32 v96, v50, v96
	v_add_f32_e32 v134, v51, v134
	v_add_f32_e32 v97, v52, v97
	v_add_f32_e32 v135, v53, v135
	v_mul_f32_e32 v94, 0xbfb8aa3b, v94
	v_mul_f32_e32 v133, 0xbfb8aa3b, v133
	v_mul_f32_e32 v96, 0xbfb8aa3b, v96
	v_mul_f32_e32 v134, 0xbfb8aa3b, v134
	v_mul_f32_e32 v97, 0xbfb8aa3b, v97
	v_mul_f32_e32 v135, 0xbfb8aa3b, v135
	v_exp_f32_e32 v94, v94
	v_exp_f32_e32 v133, v133
	v_exp_f32_e32 v96, v96
	v_exp_f32_e32 v134, v134
	v_exp_f32_e32 v97, v97
	v_exp_f32_e32 v135, v135
	v_add_f32_e32 v94, 1.0, v94
	v_add_f32_e32 v133, 1.0, v133
	v_add_f32_e32 v96, 1.0, v96
	v_add_f32_e32 v98, 1.0, v134
	v_add_f32_e32 v134, 1.0, v97
	v_add_f32_e32 v135, 1.0, v135
	v_rcp_f32_e32 v94, v94
	v_rcp_f32_e32 v132, v132
	v_rcp_f32_e32 v133, v133
	v_rcp_f32_e32 v96, v96
	v_rcp_f32_e32 v134, v134
	v_rcp_f32_e32 v135, v135
	v_rcp_f32_e32 v97, v98
	v_lshl_add_u64 v[142:143], v[142:143], 1, s[50:51]
	v_pk_fma_f32 v[64:65], v[64:65], v[132:133], v[138:139]
	v_pk_fma_f32 v[62:63], v[62:63], v[94:95], v[136:137]
	v_pk_fma_f32 v[56:57], v[56:57], v[134:135], v[130:131]
	v_pk_fma_f32 v[54:55], v[54:55], v[96:97], v[128:129]
	s_and_b64 vcc, exec, s[8:9]
	s_mov_b64 s[28:29], -1
	s_cbranch_vccnz .LBB9_190
	v_cvt_pk_bf16_f32 v128, v62, v63
	v_cvt_pk_bf16_f32 v129, v64, v65
	v_cvt_pk_bf16_f32 v130, v54, v55
	v_cvt_pk_bf16_f32 v131, v56, v57
	s_mov_b64 s[28:29], 0
	global_store_dwordx4 v[142:143], v[128:131], off
.LBB9_190:
	s_andn2_b64 vcc, exec, s[28:29]
	s_cbranch_vccnz .LBB9_192
	global_store_dwordx4 v[140:141], v[62:65], off
	global_store_dwordx4 v[140:141], v[54:57], off offset:16
.LBB9_192:
	s_waitcnt vmcnt(0)
	s_nop 0
	v_lshlrev_b32_e32 v54, 16, v120
	v_and_b32_e32 v55, 0xffff0000, v120
	v_lshlrev_b32_e32 v56, 16, v121
	v_and_b32_e32 v57, 0xffff0000, v121
	v_lshlrev_b32_e32 v62, 16, v122
	v_and_b32_e32 v63, 0xffff0000, v122
	v_lshlrev_b32_e32 v64, 16, v123
	v_and_b32_e32 v65, 0xffff0000, v123
	v_add_f32_e32 v54, v46, v54
	v_add_f32_e32 v55, v47, v55
	v_add_f32_e32 v56, v48, v56
	v_add_f32_e32 v57, v49, v57
	v_add_f32_e32 v62, v42, v62
	v_add_f32_e32 v63, v43, v63
	v_add_f32_e32 v64, v44, v64
	v_add_f32_e32 v65, v45, v65
	v_mul_f32_e32 v54, 0xbfb8aa3b, v54
	v_mul_f32_e32 v55, 0xbfb8aa3b, v55
	v_mul_f32_e32 v56, 0xbfb8aa3b, v56
	v_mul_f32_e32 v57, 0xbfb8aa3b, v57
	v_mul_f32_e32 v62, 0xbfb8aa3b, v62
	v_mul_f32_e32 v63, 0xbfb8aa3b, v63
	v_mul_f32_e32 v64, 0xbfb8aa3b, v64
	v_mul_f32_e32 v65, 0xbfb8aa3b, v65
	v_exp_f32_e32 v54, v54
	v_exp_f32_e32 v55, v55
	v_exp_f32_e32 v56, v56
	v_exp_f32_e32 v57, v57
	v_exp_f32_e32 v62, v62
	v_exp_f32_e32 v63, v63
	v_exp_f32_e32 v64, v64
	v_exp_f32_e32 v65, v65
	v_add_f32_e32 v54, 1.0, v54
	v_add_f32_e32 v55, 1.0, v55
	v_add_f32_e32 v56, 1.0, v56
	v_add_f32_e32 v57, 1.0, v57
	v_add_f32_e32 v62, 1.0, v62
	v_add_f32_e32 v63, 1.0, v63
	v_add_f32_e32 v64, 1.0, v64
	v_add_f32_e32 v65, 1.0, v65
	v_rcp_f32_e32 v54, v54
	v_rcp_f32_e32 v55, v55
	v_rcp_f32_e32 v56, v56
	v_rcp_f32_e32 v57, v57
	v_rcp_f32_e32 v62, v62
	v_rcp_f32_e32 v64, v64
	v_rcp_f32_e32 v65, v65
	v_rcp_f32_e32 v63, v63
	v_pk_fma_f32 v[40:41], v[40:41], v[56:57], v[126:127]
	v_pk_fma_f32 v[38:39], v[38:39], v[54:55], v[124:125]
	v_pk_fma_f32 v[36:37], v[36:37], v[64:65], v[118:119]
	v_pk_fma_f32 v[34:35], v[34:35], v[62:63], v[116:117]
	s_and_b64 vcc, exec, s[8:9]
	s_mov_b64 s[28:29], -1
	s_cbranch_vccnz .LBB9_194
	v_cvt_pk_bf16_f32 v54, v38, v39
	v_cvt_pk_bf16_f32 v55, v40, v41
	v_cvt_pk_bf16_f32 v56, v34, v35
	v_cvt_pk_bf16_f32 v57, v36, v37
	s_mov_b64 s[28:29], 0
	global_store_dwordx4 v[142:143], v[54:57], off offset:256
.LBB9_194:
	s_andn2_b64 vcc, exec, s[28:29]
	s_cbranch_vccnz .LBB9_196
	global_store_dwordx4 v[140:141], v[38:41], off offset:512
	global_store_dwordx4 v[140:141], v[34:37], off offset:528

.LBB9_204:
	s_nop 1
	v_add_u32_e32 v86, 0xb0, v184
	v_ashrrev_i32_e32 v87, 31, v86
	v_lshlrev_b64 v[84:85], 13, v[86:87]
	v_lshl_add_u64 v[84:85], v[180:181], 0, v[84:85]
	global_load_dwordx4 v[100:103], v[84:85], off
	s_and_b64 vcc, exec, s[6:7]
	s_mov_b64 s[28:29], -1
	s_cbranch_vccnz .LBB9_214
	s_mov_b64 s[28:29], 0
.LBB9_214:
	v_lshlrev_b64 v[86:87], 10, v[86:87]
	v_lshl_add_u64 v[110:111], v[86:87], 0, v[182:183]
	v_lshl_add_u64 v[108:109], v[110:111], 2, s[18:19]
	v_mov_b32_e32 v96, 0
	s_andn2_b64 vcc, exec, s[28:29]
	v_mov_b32_e32 v97, 0
	v_mov_b32_e32 v98, 0
	v_mov_b32_e32 v99, 0
	v_mov_b32_e32 v104, 0
	v_mov_b32_e32 v105, 0
	v_mov_b32_e32 v106, 0
	v_mov_b32_e32 v107, 0
	s_cbranch_vccnz .LBB9_216
	global_load_dwordx4 v[96:99], v[108:109], off offset:16
	global_load_dwordx4 v[104:107], v[108:109], off
.LBB9_216:
	global_load_dwordx4 v[88:91], v[84:85], off offset:256
	s_and_b64 vcc, exec, s[6:7]
	s_mov_b64 s[6:7], -1
	s_cbranch_vccnz .LBB9_218
	s_mov_b64 s[6:7], 0
.LBB9_218:
	v_mov_b32_e32 v84, 0
	s_andn2_b64 vcc, exec, s[6:7]
	v_mov_b32_e32 v85, 0
	v_mov_b32_e32 v86, 0
	v_mov_b32_e32 v87, 0
	v_mov_b32_e32 v92, 0
	v_mov_b32_e32 v93, 0
	v_mov_b32_e32 v94, 0
	v_mov_b32_e32 v95, 0
	s_cbranch_vccnz .LBB9_220
	global_load_dwordx4 v[84:87], v[108:109], off offset:528
	global_load_dwordx4 v[92:95], v[108:109], off offset:512
.LBB9_220:
	s_waitcnt vmcnt(1)
	v_lshlrev_b32_e32 v78, 16, v66
	v_and_b32_e32 v66, 0xffff0000, v66
	v_add_f32_e32 v66, v59, v66
	v_lshlrev_b32_e32 v79, 16, v67
	v_mul_f32_e32 v66, 0xbfb8aa3b, v66
	v_add_f32_e32 v79, v60, v79
	v_exp_f32_e32 v66, v66
	v_mul_f32_e32 v79, 0xbfb8aa3b, v79
	v_exp_f32_e32 v80, v79
	v_and_b32_e32 v67, 0xffff0000, v67
	v_add_f32_e32 v66, 1.0, v66
	v_rcp_f32_e32 v79, v66
	v_add_f32_e32 v66, 1.0, v80
	v_lshlrev_b32_e32 v80, 16, v68
	v_and_b32_e32 v68, 0xffff0000, v68
	v_lshlrev_b32_e32 v81, 16, v69
	v_and_b32_e32 v69, 0xffff0000, v69
	v_add_f32_e32 v78, v58, v78
	v_add_f32_e32 v67, v61, v67
	v_add_f32_e32 v80, v50, v80
	v_add_f32_e32 v68, v51, v68
	v_add_f32_e32 v81, v52, v81
	v_add_f32_e32 v69, v53, v69
	v_mul_f32_e32 v78, 0xbfb8aa3b, v78
	v_mul_f32_e32 v67, 0xbfb8aa3b, v67
	v_mul_f32_e32 v80, 0xbfb8aa3b, v80
	v_mul_f32_e32 v68, 0xbfb8aa3b, v68
	v_mul_f32_e32 v81, 0xbfb8aa3b, v81
	v_mul_f32_e32 v69, 0xbfb8aa3b, v69
	v_exp_f32_e32 v78, v78
	v_exp_f32_e32 v67, v67
	v_exp_f32_e32 v80, v80
	v_exp_f32_e32 v68, v68
	v_exp_f32_e32 v81, v81
	v_exp_f32_e32 v69, v69
	v_add_f32_e32 v78, 1.0, v78
	v_add_f32_e32 v67, 1.0, v67
	v_add_f32_e32 v80, 1.0, v80
	v_add_f32_e32 v82, 1.0, v68
	v_add_f32_e32 v68, 1.0, v81
	v_add_f32_e32 v69, 1.0, v69
	v_rcp_f32_e32 v78, v78
	v_rcp_f32_e32 v66, v66
	v_rcp_f32_e32 v67, v67
	v_rcp_f32_e32 v80, v80
	v_rcp_f32_e32 v68, v68
	v_rcp_f32_e32 v69, v69
	v_rcp_f32_e32 v81, v82
	v_lshl_add_u64 v[76:77], v[76:77], 1, s[50:51]
	v_pk_fma_f32 v[32:33], v[32:33], v[66:67], v[72:73]
	v_pk_fma_f32 v[30:31], v[30:31], v[78:79], v[70:71]
	v_pk_fma_f32 v[28:29], v[28:29], v[68:69], v[64:65]
	v_pk_fma_f32 v[26:27], v[26:27], v[80:81], v[62:63]
	s_and_b64 vcc, exec, s[8:9]
	s_mov_b64 s[28:29], -1
	s_cbranch_vccnz .LBB9_206
	v_cvt_pk_bf16_f32 v62, v30, v31
	v_cvt_pk_bf16_f32 v63, v32, v33
	v_cvt_pk_bf16_f32 v64, v26, v27
	v_cvt_pk_bf16_f32 v65, v28, v29
	s_mov_b64 s[28:29], 0
	global_store_dwordx4 v[76:77], v[62:65], off
.LBB9_206:
	s_andn2_b64 vcc, exec, s[28:29]
	s_cbranch_vccnz .LBB9_208
	global_store_dwordx4 v[74:75], v[30:33], off
	global_store_dwordx4 v[74:75], v[26:29], off offset:16
.LBB9_208:
	s_waitcnt vmcnt(0)
	s_nop 0
	v_lshlrev_b32_e32 v26, 16, v38
	v_and_b32_e32 v27, 0xffff0000, v38
	v_lshlrev_b32_e32 v28, 16, v39
	v_and_b32_e32 v29, 0xffff0000, v39
	v_lshlrev_b32_e32 v30, 16, v40
	v_and_b32_e32 v31, 0xffff0000, v40
	v_lshlrev_b32_e32 v32, 16, v41
	v_and_b32_e32 v33, 0xffff0000, v41
	v_add_f32_e32 v26, v46, v26
	v_add_f32_e32 v27, v47, v27
	v_add_f32_e32 v28, v48, v28
	v_add_f32_e32 v29, v49, v29
	v_add_f32_e32 v30, v42, v30
	v_add_f32_e32 v31, v43, v31
	v_add_f32_e32 v32, v44, v32
	v_add_f32_e32 v33, v45, v33
	v_mul_f32_e32 v26, 0xbfb8aa3b, v26
	v_mul_f32_e32 v27, 0xbfb8aa3b, v27
	v_mul_f32_e32 v28, 0xbfb8aa3b, v28
	v_mul_f32_e32 v29, 0xbfb8aa3b, v29
	v_mul_f32_e32 v30, 0xbfb8aa3b, v30
	v_mul_f32_e32 v31, 0xbfb8aa3b, v31
	v_mul_f32_e32 v32, 0xbfb8aa3b, v32
	v_mul_f32_e32 v33, 0xbfb8aa3b, v33
	v_exp_f32_e32 v26, v26
	v_exp_f32_e32 v27, v27
	v_exp_f32_e32 v28, v28
	v_exp_f32_e32 v29, v29
	v_exp_f32_e32 v30, v30
	v_exp_f32_e32 v31, v31
	v_exp_f32_e32 v32, v32
	v_exp_f32_e32 v33, v33
	v_add_f32_e32 v26, 1.0, v26
	v_add_f32_e32 v27, 1.0, v27
	v_add_f32_e32 v28, 1.0, v28
	v_add_f32_e32 v29, 1.0, v29
	v_add_f32_e32 v30, 1.0, v30
	v_add_f32_e32 v31, 1.0, v31
	v_add_f32_e32 v32, 1.0, v32
	v_add_f32_e32 v33, 1.0, v33
	v_rcp_f32_e32 v26, v26
	v_rcp_f32_e32 v27, v27
	v_rcp_f32_e32 v28, v28
	v_rcp_f32_e32 v29, v29
	v_rcp_f32_e32 v30, v30
	v_rcp_f32_e32 v32, v32
	v_rcp_f32_e32 v33, v33
	v_rcp_f32_e32 v31, v31
	v_pk_fma_f32 v[24:25], v[24:25], v[28:29], v[56:57]
	v_pk_fma_f32 v[22:23], v[22:23], v[26:27], v[54:55]
	v_pk_fma_f32 v[20:21], v[20:21], v[32:33], v[36:37]
	v_pk_fma_f32 v[18:19], v[18:19], v[30:31], v[34:35]
	s_and_b64 vcc, exec, s[8:9]
	s_mov_b64 s[28:29], -1
	s_cbranch_vccnz .LBB9_210
	v_cvt_pk_bf16_f32 v26, v22, v23
	v_cvt_pk_bf16_f32 v27, v24, v25
	v_cvt_pk_bf16_f32 v28, v18, v19
	v_bfe_u32 v29, v20, 16, 1
	v_add3_u32 v29, v20, v29, s1
	v_bfe_u32 v30, v21, 16, 1
	v_lshrrev_b32_e32 v29, 16, v29
	v_add3_u32 v30, v21, v30, s1
	v_and_or_b32 v29, v30, s68, v29
	s_mov_b64 s[28:29], 0
	global_store_dwordx4 v[76:77], v[26:29], off offset:256

.LBB9_212:
	s_waitcnt vmcnt(1)
	v_lshlrev_b32_e32 v62, 16, v100
	v_and_b32_e32 v100, 0xffff0000, v100
	v_add_f32_e32 v100, v59, v100
	v_lshlrev_b32_e32 v59, 16, v101
	v_mul_f32_e32 v100, 0xbfb8aa3b, v100
	v_add_f32_e32 v59, v60, v59
	v_exp_f32_e32 v100, v100
	v_mul_f32_e32 v59, 0xbfb8aa3b, v59
	v_exp_f32_e32 v60, v59
	v_and_b32_e32 v101, 0xffff0000, v101
	v_add_f32_e32 v100, 1.0, v100
	v_rcp_f32_e32 v59, v100
	v_add_f32_e32 v100, 1.0, v60
	v_lshlrev_b32_e32 v60, 16, v102
	v_and_b32_e32 v102, 0xffff0000, v102
	v_add_f32_e32 v102, v51, v102
	v_lshlrev_b32_e32 v51, 16, v103
	v_and_b32_e32 v103, 0xffff0000, v103
	v_add_f32_e32 v58, v58, v62
	v_add_f32_e32 v101, v61, v101
	v_add_f32_e32 v50, v50, v60
	v_add_f32_e32 v51, v52, v51
	v_add_f32_e32 v103, v53, v103
	v_mul_f32_e32 v58, 0xbfb8aa3b, v58
	v_mul_f32_e32 v101, 0xbfb8aa3b, v101
	v_mul_f32_e32 v50, 0xbfb8aa3b, v50
	v_mul_f32_e32 v102, 0xbfb8aa3b, v102
	v_mul_f32_e32 v51, 0xbfb8aa3b, v51
	v_mul_f32_e32 v103, 0xbfb8aa3b, v103
	v_exp_f32_e32 v58, v58
	v_exp_f32_e32 v101, v101
	v_exp_f32_e32 v50, v50
	v_exp_f32_e32 v102, v102
	v_exp_f32_e32 v51, v51
	v_exp_f32_e32 v103, v103
	v_add_f32_e32 v58, 1.0, v58
	v_add_f32_e32 v101, 1.0, v101
	v_add_f32_e32 v50, 1.0, v50
	v_add_f32_e32 v52, 1.0, v102
	v_add_f32_e32 v102, 1.0, v51
	v_add_f32_e32 v103, 1.0, v103
	v_rcp_f32_e32 v58, v58
	v_rcp_f32_e32 v100, v100
	v_rcp_f32_e32 v101, v101
	v_rcp_f32_e32 v50, v50
	v_rcp_f32_e32 v102, v102
	v_rcp_f32_e32 v103, v103
	v_rcp_f32_e32 v51, v52
	v_lshl_add_u64 v[110:111], v[110:111], 1, s[50:51]
	v_pk_fma_f32 v[16:17], v[16:17], v[100:101], v[106:107]
	v_pk_fma_f32 v[14:15], v[14:15], v[58:59], v[104:105]
	v_pk_fma_f32 v[12:13], v[12:13], v[102:103], v[98:99]
	v_pk_fma_f32 v[10:11], v[10:11], v[50:51], v[96:97]
	s_and_b64 vcc, exec, s[8:9]
	s_mov_b64 s[6:7], -1
	s_cbranch_vccnz .LBB9_222
	v_cvt_pk_bf16_f32 v96, v14, v15
	v_cvt_pk_bf16_f32 v97, v16, v17
	v_cvt_pk_bf16_f32 v98, v10, v11
	v_cvt_pk_bf16_f32 v99, v12, v13
	s_mov_b64 s[6:7], 0
	global_store_dwordx4 v[110:111], v[96:99], off
.LBB9_222:
	s_andn2_b64 vcc, exec, s[6:7]
	s_cbranch_vccnz .LBB9_224
	global_store_dwordx4 v[108:109], v[14:17], off
	global_store_dwordx4 v[108:109], v[10:13], off offset:16
.LBB9_224:
	s_waitcnt vmcnt(0)
	s_nop 0
	v_lshlrev_b32_e32 v10, 16, v88
	v_and_b32_e32 v11, 0xffff0000, v88
	v_lshlrev_b32_e32 v12, 16, v89
	v_and_b32_e32 v13, 0xffff0000, v89
	v_lshlrev_b32_e32 v14, 16, v90
	v_and_b32_e32 v15, 0xffff0000, v90
	v_lshlrev_b32_e32 v16, 16, v91
	v_and_b32_e32 v17, 0xffff0000, v91
	v_add_f32_e32 v10, v46, v10
	v_add_f32_e32 v11, v47, v11
	v_add_f32_e32 v12, v48, v12
	v_add_f32_e32 v13, v49, v13
	v_add_f32_e32 v14, v42, v14
	v_add_f32_e32 v15, v43, v15
	v_add_f32_e32 v16, v44, v16
	v_add_f32_e32 v17, v45, v17
	v_mul_f32_e32 v10, 0xbfb8aa3b, v10
	v_mul_f32_e32 v11, 0xbfb8aa3b, v11
	v_mul_f32_e32 v12, 0xbfb8aa3b, v12
	v_mul_f32_e32 v13, 0xbfb8aa3b, v13
	v_mul_f32_e32 v14, 0xbfb8aa3b, v14
	v_mul_f32_e32 v15, 0xbfb8aa3b, v15
	v_mul_f32_e32 v16, 0xbfb8aa3b, v16
	v_mul_f32_e32 v17, 0xbfb8aa3b, v17
	v_exp_f32_e32 v10, v10
	v_exp_f32_e32 v11, v11
	v_exp_f32_e32 v12, v12
	v_exp_f32_e32 v13, v13
	v_exp_f32_e32 v14, v14
	v_exp_f32_e32 v15, v15
	v_exp_f32_e32 v16, v16
	v_exp_f32_e32 v17, v17
	v_add_f32_e32 v10, 1.0, v10
	v_add_f32_e32 v11, 1.0, v11
	v_add_f32_e32 v12, 1.0, v12
	v_add_f32_e32 v13, 1.0, v13
	v_add_f32_e32 v14, 1.0, v14
	v_add_f32_e32 v15, 1.0, v15
	v_add_f32_e32 v16, 1.0, v16
	v_add_f32_e32 v17, 1.0, v17
	v_rcp_f32_e32 v10, v10
	v_rcp_f32_e32 v11, v11
	v_rcp_f32_e32 v12, v12
	v_rcp_f32_e32 v13, v13
	v_rcp_f32_e32 v14, v14
	v_rcp_f32_e32 v16, v16
	v_rcp_f32_e32 v17, v17
	v_rcp_f32_e32 v15, v15
	v_pk_fma_f32 v[8:9], v[8:9], v[12:13], v[94:95]
	v_pk_fma_f32 v[6:7], v[6:7], v[10:11], v[92:93]
	v_pk_fma_f32 v[4:5], v[4:5], v[16:17], v[86:87]
	v_pk_fma_f32 v[2:3], v[2:3], v[14:15], v[84:85]
	s_and_b64 vcc, exec, s[8:9]
	s_mov_b64 s[6:7], -1
	s_cbranch_vccnz .LBB9_226
	v_cvt_pk_bf16_f32 v10, v6, v7
	v_cvt_pk_bf16_f32 v11, v8, v9
	v_cvt_pk_bf16_f32 v12, v2, v3
	v_cvt_pk_bf16_f32 v13, v4, v5
	s_mov_b64 s[6:7], 0
	global_store_dwordx4 v[110:111], v[10:13], off offset:256
.LBB9_226:
	s_andn2_b64 vcc, exec, s[6:7]
	s_cbranch_vccnz .LBB9_228
	global_store_dwordx4 v[108:109], v[6:9], off offset:512
	global_store_dwordx4 v[108:109], v[2:5], off offset:528

; __device__ __forceinline__ unsigned xb_ld(unsigned* p)              { return __hip_atomic_load(p, __ATOMIC_RELAXED, __HIP_MEMORY_SCOPE_AGENT); }
; #define XB_SPIN(cond, bar) do { unsigned _sp = 0; while (cond) { __builtin_amdgcn_s_sleep(1); \
;     if ((++_sp & 255u) == 0u) { if (xb_ld(&(bar)[XB_TMO])) break; if (_sp > XB_SPIN_CAP) { atomicAdd(&(bar)[XB_TMO], 1u); break; } } } } while (0)
; __device__ __forceinline__ void xcd_barrier(const XcdBarrier& b) {
;     ...
;             XB_SPIN(xb_ld(&bar[XB_XGEN(b.x)]) == gen, bar);
;             __builtin_amdgcn_fence(__ATOMIC_ACQUIRE, "agent");
;             asm volatile("s_waitcnt vmcnt(0)" ::: "memory");
.LBB9_856:
	s_or_b64 exec, exec, s[8:9]
	s_waitcnt vmcnt(0)
	s_nop 0
	s_waitcnt vmcnt(0)

; __device__ __forceinline__ unsigned xb_add(unsigned* p, unsigned v) { return __hip_atomic_fetch_add(p, v, __ATOMIC_RELAXED, __HIP_MEMORY_SCOPE_AGENT); }
; __device__ __forceinline__ void xcd_barrier(const XcdBarrier& b) {
;     ...
;             __builtin_amdgcn_fence(__ATOMIC_ACQUIRE, "agent");
;             xb_add(&bar[XB_XGEN(b.x)], 1u);
;             asm volatile("s_waitcnt vmcnt(0)" ::: "memory");
.LBB9_874:
	s_or_b64 exec, exec, s[6:7]
	s_mov_b64 s[6:7], exec
	v_mbcnt_lo_u32_b32 v0, s6, 0
	v_mbcnt_hi_u32_b32 v0, s7, v0
	v_cmp_eq_u32_e32 vcc, 0, v0
	s_waitcnt vmcnt(0)
	s_nop 0
	s_and_saveexec_b64 s[8:9], vcc
	s_cbranch_execz .LBB9_876
	s_bcnt1_i32_b64 s6, s[6:7]
	v_mov_b32_e32 v0, s6
	v_mov_b32_e32 v2, 0x2000
	global_atomic_add v2, v0, s[4:5] offset:1024

; __device__ __forceinline__ void xcd_barrier(const XcdBarrier& b) {
;     ...
;     }
;     __syncthreads();
.LBB9_877:
	s_or_b64 exec, exec, s[2:3]
	v_readfirstlane_b32 s100, v212
	s_lshr_b32 s100, s100, 6
	s_cmp_lg_u32 s100, 1
	s_cbranch_scc1 .Lno_early_inv
	buffer_inv sc1
	s_waitcnt vmcnt(0)
.Lno_early_inv:
	s_mov_b64 s[2:3], 0
	s_waitcnt lgkmcnt(0)
	s_barrier

; __global__ void __launch_bounds__(MEGA_THREADS, 2) mega(MArgs a) {
	.amdhsa_kernel _Z4mega5MArgs
		.amdhsa_group_segment_fixed_size 0
		.amdhsa_private_segment_fixed_size 0
		.amdhsa_kernarg_size 496
		.amdhsa_user_sgpr_count 2
		.amdhsa_user_sgpr_dispatch_ptr 0
		.amdhsa_user_sgpr_queue_ptr 0
		.amdhsa_user_sgpr_kernarg_segment_ptr 1
		.amdhsa_user_sgpr_dispatch_id 0
		.amdhsa_user_sgpr_kernarg_preload_length 0
		.amdhsa_user_sgpr_kernarg_preload_offset 0
		.amdhsa_user_sgpr_private_segment_size 0
		.amdhsa_uses_dynamic_stack 0
		.amdhsa_enable_private_segment 0
		.amdhsa_system_sgpr_workgroup_id_x 1
		.amdhsa_system_sgpr_workgroup_id_y 0
		.amdhsa_system_sgpr_workgroup_id_z 0
		.amdhsa_system_sgpr_workgroup_info 0
		.amdhsa_system_vgpr_workitem_id 2
		.amdhsa_next_free_vgpr 256
		.amdhsa_next_free_sgpr 102
		.amdhsa_accum_offset 256
		.amdhsa_reserve_vcc 1
		.amdhsa_float_round_mode_32 0
		.amdhsa_float_round_mode_16_64 0
		.amdhsa_float_denorm_mode_32 3
		.amdhsa_float_denorm_mode_16_64 3
		.amdhsa_dx10_clamp 1
		.amdhsa_ieee_mode 1
		.amdhsa_fp16_overflow 0
		.amdhsa_tg_split 0
		.amdhsa_exception_fp_ieee_invalid_op 0
		.amdhsa_exception_fp_denorm_src 0
		.amdhsa_exception_fp_ieee_div_zero 0
		.amdhsa_exception_fp_ieee_overflow 0
		.amdhsa_exception_fp_ieee_underflow 0
		.amdhsa_exception_fp_ieee_inexact 0
		.amdhsa_exception_int_div_zero 0
	.end_amdhsa_kernel

; __device__ __forceinline__ float bf2f(bf16_t b) { return __uint_as_float(((unsigned)b) << 16); }
; __device__ __forceinline__ bf16_t f2bf(float f) { unsigned u = __float_as_uint(f); return (bf16_t)((u + 0x7fffu + ((u >> 16) & 1u)) >> 16); }
; __global__ void __launch_bounds__(256) n_rmsnorm(const float* __restrict__ x, const float* __restrict__ g, bf16_t* __restrict__ H,
;                                                  const float* __restrict__ Wf, const float* __restrict__ bfg, float* __restrict__ LOGF, int nrows) {
; __global__ void __launch_bounds__(256) n_headnorm(bf16_t* X, const float* __restrict__ g, int HD, float scale) {
;     const int idx = blockIdx.x * 256 + threadIdx.x, nh = DM / HD, row = idx / nh, h = idx % nh;
;     if (row >= T) return;
;     bf16_t* p = X + (size_t)row * DM + h * HD; float ss = 0.f;
;     for (int d = 0; d < HD; ++d) { const float v = bf2f(p[d]); ss += v * v; }
;     const float rstd = rsqrtf(ss / HD + EPS) * scale;
;     for (int d = 0; d < HD; ++d) p[d] = f2bf(bf2f(p[d]) * rstd * g[d]);
; }
; __global__ void __launch_bounds__(1024) n_cumsum(const float* __restrict__ LOGF, float* __restrict__ FB) {
;     __shared__ float part[1024];
;     const int bh = blockIdx.x, tid = threadIdx.x; const float* src = LOGF + (size_t)bh * SEQ + tid * 8; float v[8]; float s = 0.f;
; #pragma unroll
;     for (int i = 0; i < 8; ++i) { s += src[i]; v[i] = s; }
;     part[tid] = s; __syncthreads();
;     if (tid == 0) { float run = 0.f; for (int i = 0; i < 1024; ++i) { const float t_ = part[i]; part[i] = run; run += t_; } }
;     __syncthreads();
;     const float off = part[tid]; float* dst = FB + (size_t)bh * SEQ + tid * 8;
; #pragma unroll
;     for (int i = 0; i < 8; ++i) dst[i] = off + v[i];
; }
; __global__ void __launch_bounds__(256) n_fox_attn(const bf16_t* Q, const bf16_t* __restrict__ K, const bf16_t* __restrict__ V, const float* __restrict__ FB, bf16_t* O) {
amdhsa.kernels:
  - .agpr_count:     0
    .args:
      - .actual_access:  read_only
        .address_space:  global
        .offset:         0
        .size:           8
        .value_kind:     global_buffer
      - .actual_access:  read_only
        .address_space:  global
        .offset:         8
        .size:           8
        .value_kind:     global_buffer
      - .actual_access:  write_only
        .address_space:  global
        .offset:         16
        .size:           8
        .value_kind:     global_buffer
      - .actual_access:  read_only
        .address_space:  global
        .offset:         24
        .size:           8
        .value_kind:     global_buffer
      - .actual_access:  read_only
        .address_space:  global
        .offset:         32
        .size:           8
        .value_kind:     global_buffer
      - .actual_access:  write_only
        .address_space:  global
        .offset:         40
        .size:           8
        .value_kind:     global_buffer
      - .offset:         48
        .size:           4
        .value_kind:     by_value
    .group_segment_fixed_size: 0
    .kernarg_segment_align: 8
    .kernarg_segment_size: 52
    .language:       OpenCL C
    .language_version:
      - 2
      - 0
    .max_flat_workgroup_size: 256
    .name:           _Z9n_rmsnormPKfS0_PtS0_S0_Pfi
    .private_segment_fixed_size: 0
    .sgpr_count:     18
    .sgpr_spill_count: 0
    .symbol:         _Z9n_rmsnormPKfS0_PtS0_S0_Pfi.kd
    .uniform_work_group_size: 1
    .uses_dynamic_stack: false
    .vgpr_count:     109
    .vgpr_spill_count: 0
    .wavefront_size: 64
  - .agpr_count:     0
    .args:
      - .address_space:  global
        .offset:         0
        .size:           8
        .value_kind:     global_buffer
      - .actual_access:  read_only
        .address_space:  global
        .offset:         8
        .size:           8
        .value_kind:     global_buffer
      - .offset:         16
        .size:           4
        .value_kind:     by_value
      - .offset:         20
        .size:           4
        .value_kind:     by_value
    .group_segment_fixed_size: 0
    .kernarg_segment_align: 8
    .kernarg_segment_size: 24
    .language:       OpenCL C
    .language_version:
      - 2
      - 0
    .max_flat_workgroup_size: 256
    .name:           _Z10n_headnormPtPKfif
    .private_segment_fixed_size: 0
    .sgpr_count:     20
    .sgpr_spill_count: 0
    .symbol:         _Z10n_headnormPtPKfif.kd
    .uniform_work_group_size: 1
    .uses_dynamic_stack: false
    .vgpr_count:     13
    .vgpr_spill_count: 0
    .wavefront_size: 64
  - .agpr_count:     0
    .args:
      - .actual_access:  read_only
        .address_space:  global
        .offset:         0
        .size:           8
        .value_kind:     global_buffer
      - .actual_access:  write_only
        .address_space:  global
        .offset:         8
        .size:           8
        .value_kind:     global_buffer
    .group_segment_fixed_size: 4096
    .kernarg_segment_align: 8
    .kernarg_segment_size: 16
    .language:       OpenCL C
    .language_version:
      - 2
      - 0
    .max_flat_workgroup_size: 1024
    .name:           _Z8n_cumsumPKfPf
    .private_segment_fixed_size: 0
    .sgpr_count:     14
    .sgpr_spill_count: 0
    .symbol:         _Z8n_cumsumPKfPf.kd
    .uniform_work_group_size: 1
    .uses_dynamic_stack: false
    .vgpr_count:     32
    .vgpr_spill_count: 0
    .wavefront_size: 64
  - .agpr_count:     0
    .args:
      - .address_space:  global
        .offset:         0
        .size:           8
        .value_kind:     global_buffer
      - .actual_access:  read_only
        .address_space:  global
        .offset:         8
        .size:           8
        .value_kind:     global_buffer
      - .actual_access:  read_only
        .address_space:  global
        .offset:         16
        .size:           8
        .value_kind:     global_buffer
      - .actual_access:  read_only
        .address_space:  global
        .offset:         24
        .size:           8
        .value_kind:     global_buffer
      - .address_space:  global
        .offset:         32
        .size:           8
        .value_kind:     global_buffer
    .group_segment_fixed_size: 33024
    .kernarg_segment_align: 8
    .kernarg_segment_size: 40
    .language:       OpenCL C
    .language_version:
      - 2
      - 0
    .max_flat_workgroup_size: 256
    .name:           _Z10n_fox_attnPKtS0_S0_PKfPt
    .private_segment_fixed_size: 0
    .sgpr_count:     38
    .sgpr_spill_count: 0
    .symbol:         _Z10n_fox_attnPKtS0_S0_PKfPt.kd
    .uniform_work_group_size: 1
    .uses_dynamic_stack: false
    .vgpr_count:     178
    .vgpr_spill_count: 0
    .wavefront_size: 64
; __device__ __forceinline__ float bf2f(bf16_t b) { return __uint_as_float(((unsigned)b) << 16); }
; __device__ __forceinline__ bf16_t f2bf(float f) { unsigned u = __float_as_uint(f); return (bf16_t)((u + 0x7fffu + ((u >> 16) & 1u)) >> 16); }
; __device__ __forceinline__ float softplusf(float x) { return fmaxf(x, 0.f) + log1pf(__expf(-fabsf(x))); }
; __global__ void __launch_bounds__(256) n_sb_attn(const bf16_t* Q, const bf16_t* __restrict__ K, const bf16_t* __restrict__ V, bf16_t* O) {
;     __shared__ float Ks[64][64], Vs[64][64];
;     const int bh = blockIdx.y, b = bh >> 4, h = bh & 15, tq = blockIdx.x * 256 + threadIdx.x;
;     const size_t rowq = (size_t)b * SEQ + tq;
;     float q[64], o[64];
; #pragma unroll
;     for (int d = 0; d < 64; ++d) { q[d] = bf2f(Q[rowq * DM + h * 64 + d]) * 0.125f; o[d] = 0.f; }
;     float R = 0.f;
;     ...
;         if (__syncthreads_and(R < SB_THR)) break;
;         for (int i = threadIdx.x; i < 64 * 64; i += 256) { const int r = i >> 6, c = i & 63; const size_t rk = ((size_t)b * SEQ + kt * 64 + r) * DM + h * 64 + c; Ks[r][c] = bf2f(K[rk]); Vs[r][c] = bf2f(V[rk]); }
;         __syncthreads();
;         for (int j = 63; j >= 0; --j) {
;             const int s = kt * 64 + j; if (s >= tq) continue;
;             float z = 0.f;
; #pragma unroll
;             for (int d = 0; d < 64; ++d) z += q[d] * Ks[j][d];
;             const float sp = softplusf(z);
;             const float w = __expf((z - sp) + R);
;             R -= sp;
; #pragma unroll
;             for (int d = 0; d < 64; ++d) o[d] += w * Vs[j][d];
;         }
;     }
; #pragma unroll
;     for (int d = 0; d < 64; ++d) O[rowq * DM + h * 64 + d] = f2bf(o[d]);
; }
; __global__ void __launch_bounds__(64) n_lru(const bf16_t* LX, const bf16_t* __restrict__ LG, const float* __restrict__ cw, const float* __restrict__ cb, ...
; __global__ void __launch_bounds__(256) n_memkv_post(const float* __restrict__ raw, const float* __restrict__ gk, const float* __restrict__ gq, bf16_t* __restrict__ MK, bf16_t* __restrict__ MVT) {
  - .agpr_count:     0
    .args:
      - .address_space:  global
        .offset:         0
        .size:           8
        .value_kind:     global_buffer
      - .actual_access:  read_only
        .address_space:  global
        .offset:         8
        .size:           8
        .value_kind:     global_buffer
      - .actual_access:  read_only
        .address_space:  global
        .offset:         16
        .size:           8
        .value_kind:     global_buffer
      - .address_space:  global
        .offset:         24
        .size:           8
        .value_kind:     global_buffer
      - .offset:         32
        .size:           4
        .value_kind:     hidden_block_count_x
      - .offset:         36
        .size:           4
        .value_kind:     hidden_block_count_y
      - .offset:         40
        .size:           4
        .value_kind:     hidden_block_count_z
      - .offset:         44
        .size:           2
        .value_kind:     hidden_group_size_x
      - .offset:         46
        .size:           2
        .value_kind:     hidden_group_size_y
      - .offset:         48
        .size:           2
        .value_kind:     hidden_group_size_z
      - .offset:         50
        .size:           2
        .value_kind:     hidden_remainder_x
      - .offset:         52
        .size:           2
        .value_kind:     hidden_remainder_y
      - .offset:         54
        .size:           2
        .value_kind:     hidden_remainder_z
      - .offset:         72
        .size:           8
        .value_kind:     hidden_global_offset_x
      - .offset:         80
        .size:           8
        .value_kind:     hidden_global_offset_y
      - .offset:         88
        .size:           8
        .value_kind:     hidden_global_offset_z
      - .offset:         96
        .size:           2
        .value_kind:     hidden_grid_dims
    .group_segment_fixed_size: 33024
    .kernarg_segment_align: 8
    .kernarg_segment_size: 288
    .language:       OpenCL C
    .language_version:
      - 2
      - 0
    .max_flat_workgroup_size: 256
    .name:           _Z9n_sb_attnPKtS0_S0_Pt
    .private_segment_fixed_size: 0
    .sgpr_count:     41
    .sgpr_spill_count: 0
    .symbol:         _Z9n_sb_attnPKtS0_S0_Pt.kd
    .uniform_work_group_size: 1
    .uses_dynamic_stack: false
    .vgpr_count:     178
    .vgpr_spill_count: 0
    .wavefront_size: 64
  - .agpr_count:     0
    .args:
      - .address_space:  global
        .offset:         0
        .size:           8
        .value_kind:     global_buffer
      - .actual_access:  read_only
        .address_space:  global
        .offset:         8
        .size:           8
        .value_kind:     global_buffer
      - .actual_access:  read_only
        .address_space:  global
        .offset:         16
        .size:           8
        .value_kind:     global_buffer
      - .actual_access:  read_only
        .address_space:  global
        .offset:         24
        .size:           8
        .value_kind:     global_buffer
      - .actual_access:  read_only
        .address_space:  global
        .offset:         32
        .size:           8
        .value_kind:     global_buffer
      - .actual_access:  read_only
        .address_space:  global
        .offset:         40
        .size:           8
        .value_kind:     global_buffer
      - .actual_access:  read_only
        .address_space:  global
        .offset:         48
        .size:           8
        .value_kind:     global_buffer
      - .actual_access:  read_only
        .address_space:  global
        .offset:         56
        .size:           8
        .value_kind:     global_buffer
      - .actual_access:  read_only
        .address_space:  global
        .offset:         64
        .size:           8
        .value_kind:     global_buffer
      - .address_space:  global
        .offset:         72
        .size:           8
        .value_kind:     global_buffer
    .group_segment_fixed_size: 256
    .kernarg_segment_align: 8
    .kernarg_segment_size: 80
    .language:       OpenCL C
    .language_version:
      - 2
      - 0
    .max_flat_workgroup_size: 64
    .name:           _Z5n_lruPKtS0_PKfS2_S2_S2_S2_S2_S2_Pt
    .private_segment_fixed_size: 0
    .sgpr_count:     30
    .sgpr_spill_count: 0
    .symbol:         _Z5n_lruPKtS0_PKfS2_S2_S2_S2_S2_S2_Pt.kd
    .uniform_work_group_size: 1
    .uses_dynamic_stack: false
    .vgpr_count:     225
    .vgpr_spill_count: 0
    .wavefront_size: 64
  - .agpr_count:     0
    .args:
      - .actual_access:  read_only
        .address_space:  global
        .offset:         0
        .size:           8
        .value_kind:     global_buffer
      - .actual_access:  read_only
        .address_space:  global
        .offset:         8
        .size:           8
        .value_kind:     global_buffer
      - .actual_access:  read_only
        .address_space:  global
        .offset:         16
        .size:           8
        .value_kind:     global_buffer
      - .actual_access:  write_only
        .address_space:  global
        .offset:         24
        .size:           8
        .value_kind:     global_buffer
      - .actual_access:  write_only
        .address_space:  global
        .offset:         32
        .size:           8
        .value_kind:     global_buffer
    .group_segment_fixed_size: 16
    .kernarg_segment_align: 8
    .kernarg_segment_size: 40
    .language:       OpenCL C
    .language_version:
      - 2
      - 0
    .max_flat_workgroup_size: 256
    .name:           _Z12n_memkv_postPKfS0_S0_PtS1_
    .private_segment_fixed_size: 0
    .sgpr_count:     20
    .sgpr_spill_count: 0
    .symbol:         _Z12n_memkv_postPKfS0_S0_PtS1_.kd
    .uniform_work_group_size: 1
    .uses_dynamic_stack: false
    .vgpr_count:     27
    .vgpr_spill_count: 0
    .wavefront_size: 64
; __device__ __forceinline__ float bf2f(bf16_t b) { return __uint_as_float(((unsigned)b) << 16); }
; __device__ __forceinline__ bf16_t f2bf(float f) { unsigned u = __float_as_uint(f); return (bf16_t)((u + 0x7fffu + ((u >> 16) & 1u)) >> 16); }
; __global__ void __launch_bounds__(256) n_mem_attn(const bf16_t* MQ, const bf16_t* __restrict__ MK, const bf16_t* __restrict__ MVT, bf16_t* YM) {
;     __shared__ float qs[256], ps[256], red[4];
;     const int row = blockIdx.x >> 2, h = blockIdx.x & 3, b = row / SEQ, tid = threadIdx.x;
;     const float qv = bf2f(MQ[(size_t)row * DM + h * 256 + tid]);
;     float ss = wave_sum(qv * qv);
;     if ((tid & 63) == 0) red[tid >> 6] = ss;
;     qs[tid] = qv;
;     __syncthreads();
;     const float rstd = rsqrtf((red[0] + red[1] + red[2] + red[3]) * (1.f / 256.f) + EPS);
;     const bf16_t* kr = MK + ((size_t)b * 256 + tid) * DM + h * 256;
;     float s = 0.f;
;     for (int d = 0; d < 256; ++d) s += qs[d] * bf2f(kr[d]);
;     s *= rstd * (1.f / 16.f);
;     __syncthreads();
;     float mx = s;
; #pragma unroll
;     for (int o = 1; o < 64; o <<= 1) mx = fmaxf(mx, __shfl_xor(mx, o));
;     if ((tid & 63) == 0) red[tid >> 6] = mx;
;     __syncthreads();
;     mx = fmaxf(fmaxf(red[0], red[1]), fmaxf(red[2], red[3]));
;     const float p = __expf(s - mx);
;     ps[tid] = p;
;     float sum = wave_sum(p);
;     __syncthreads();
;     if ((tid & 63) == 0) red[tid >> 6] = sum;
;     __syncthreads();
;     sum = red[0] + red[1] + red[2] + red[3];
;     const bf16_t* vr = MVT + (((size_t)b * 4 + h) * 256 + tid) * 256;
;     float o = 0.f;
;     for (int m = 0; m < 256; ++m) o += ps[m] * bf2f(vr[m]);
;     YM[(size_t)row * DM + h * 256 + tid] = f2bf(o / sum);
; }
; __global__ void __launch_bounds__(256) n_act(const bf16_t* __restrict__ GV, const float* __restrict__ cw, const float* __restrict__ cb, bf16_t* __restrict__ ACT) {
; __global__ void __launch_bounds__(MEGA_THREADS, 2) mega(MArgs a) {
  - .agpr_count:     0
    .args:
      - .address_space:  global
        .offset:         0
        .size:           8
        .value_kind:     global_buffer
      - .actual_access:  read_only
        .address_space:  global
        .offset:         8
        .size:           8
        .value_kind:     global_buffer
      - .actual_access:  read_only
        .address_space:  global
        .offset:         16
        .size:           8
        .value_kind:     global_buffer
      - .address_space:  global
        .offset:         24
        .size:           8
        .value_kind:     global_buffer
    .group_segment_fixed_size: 2064
    .kernarg_segment_align: 8
    .kernarg_segment_size: 32
    .language:       OpenCL C
    .language_version:
      - 2
      - 0
    .max_flat_workgroup_size: 256
    .name:           _Z10n_mem_attnPKtS0_S0_Pt
    .private_segment_fixed_size: 0
    .sgpr_count:     20
    .sgpr_spill_count: 0
    .symbol:         _Z10n_mem_attnPKtS0_S0_Pt.kd
    .uniform_work_group_size: 1
    .uses_dynamic_stack: false
    .vgpr_count:     50
    .vgpr_spill_count: 0
    .wavefront_size: 64
  - .agpr_count:     0
    .args:
      - .actual_access:  read_only
        .address_space:  global
        .offset:         0
        .size:           8
        .value_kind:     global_buffer
      - .actual_access:  read_only
        .address_space:  global
        .offset:         8
        .size:           8
        .value_kind:     global_buffer
      - .actual_access:  read_only
        .address_space:  global
        .offset:         16
        .size:           8
        .value_kind:     global_buffer
      - .actual_access:  write_only
        .address_space:  global
        .offset:         24
        .size:           8
        .value_kind:     global_buffer
    .group_segment_fixed_size: 0
    .kernarg_segment_align: 8
    .kernarg_segment_size: 32
    .language:       OpenCL C
    .language_version:
      - 2
      - 0
    .max_flat_workgroup_size: 256
    .name:           _Z5n_actPKtPKfS2_Pt
    .private_segment_fixed_size: 0
    .sgpr_count:     14
    .sgpr_spill_count: 0
    .symbol:         _Z5n_actPKtPKfS2_Pt.kd
    .uniform_work_group_size: 1
    .uses_dynamic_stack: false
    .vgpr_count:     17
    .vgpr_spill_count: 0
    .wavefront_size: 64
  - .agpr_count:     0
    .args:
      - .offset:         0
        .size:           240
        .value_kind:     by_value
      - .offset:         240
        .size:           4
        .value_kind:     hidden_block_count_x
      - .offset:         244
        .size:           4
        .value_kind:     hidden_block_count_y
      - .offset:         248
        .size:           4
        .value_kind:     hidden_block_count_z
      - .offset:         252
        .size:           2
        .value_kind:     hidden_group_size_x
      - .offset:         254
        .size:           2
        .value_kind:     hidden_group_size_y
      - .offset:         256
        .size:           2
        .value_kind:     hidden_group_size_z
      - .offset:         258
        .size:           2
        .value_kind:     hidden_remainder_x
      - .offset:         260
        .size:           2
        .value_kind:     hidden_remainder_y
      - .offset:         262
        .size:           2
        .value_kind:     hidden_remainder_z
      - .offset:         280
        .size:           8
        .value_kind:     hidden_global_offset_x
      - .offset:         288
        .size:           8
        .value_kind:     hidden_global_offset_y
      - .offset:         296
        .size:           8
        .value_kind:     hidden_global_offset_z
      - .offset:         304
        .size:           2
        .value_kind:     hidden_grid_dims
      - .offset:         328
        .size:           8
        .value_kind:     hidden_multigrid_sync_arg
      - .offset:         360
        .size:           4
        .value_kind:     hidden_dynamic_lds_size
    .group_segment_fixed_size: 0
    .kernarg_segment_align: 8
    .kernarg_segment_size: 496
    .language:       OpenCL C
    .language_version:
      - 2
      - 0
    .max_flat_workgroup_size: 512
    .name:           _Z4mega5MArgs
    .private_segment_fixed_size: 0
    .sgpr_count:     108
    .sgpr_spill_count: 101
    .symbol:         _Z4mega5MArgs.kd
    .uniform_work_group_size: 1
    .uses_dynamic_stack: false
    .vgpr_count:     256
    .vgpr_spill_count: 0
    .wavefront_size: 64
; template <class Epi> __global__ void __launch_bounds__(256) n_gemm(const bf16_t* __restrict__ A, const float* __restrict__ W, int lda, int ldw, int K, int kmask, Epi epi) {
  - .agpr_count:     0
    .args:
      - .actual_access:  read_only
        .address_space:  global
        .offset:         0
        .size:           8
        .value_kind:     global_buffer
      - .actual_access:  read_only
        .address_space:  global
        .offset:         8
        .size:           8
        .value_kind:     global_buffer
      - .offset:         16
        .size:           4
        .value_kind:     by_value
      - .offset:         20
        .size:           4
        .value_kind:     by_value
      - .offset:         24
        .size:           4
        .value_kind:     by_value
      - .offset:         28
        .size:           4
        .value_kind:     by_value
      - .offset:         32
        .size:           16
        .value_kind:     by_value
    .group_segment_fixed_size: 8704
    .kernarg_segment_align: 8
    .kernarg_segment_size: 48
    .language:       OpenCL C
    .language_version:
      - 2
      - 0
    .max_flat_workgroup_size: 256
    .name:           _Z6n_gemmI9EStoreF32EvPKtPKfiiiiT_
    .private_segment_fixed_size: 0
    .sgpr_count:     24
    .sgpr_spill_count: 0
    .symbol:         _Z6n_gemmI9EStoreF32EvPKtPKfiiiiT_.kd
    .uniform_work_group_size: 1
    .uses_dynamic_stack: false
    .vgpr_count:     66
    .vgpr_spill_count: 0
    .wavefront_size: 64
  - .agpr_count:     0
    .args:
      - .actual_access:  read_only
        .address_space:  global
        .offset:         0
        .size:           8
        .value_kind:     global_buffer
      - .actual_access:  read_only
        .address_space:  global
        .offset:         8
        .size:           8
        .value_kind:     global_buffer
      - .offset:         16
        .size:           4
        .value_kind:     by_value
      - .offset:         20
        .size:           4
        .value_kind:     by_value
      - .offset:         24
        .size:           4
        .value_kind:     by_value
      - .offset:         28
        .size:           4
        .value_kind:     by_value
      - .offset:         32
        .size:           16
        .value_kind:     by_value
    .group_segment_fixed_size: 8704
    .kernarg_segment_align: 8
    .kernarg_segment_size: 48
    .language:       OpenCL C
    .language_version:
      - 2
      - 0
    .max_flat_workgroup_size: 256
    .name:           _Z6n_gemmI10EStoreBf16EvPKtPKfiiiiT_
    .private_segment_fixed_size: 0
    .sgpr_count:     24
    .sgpr_spill_count: 0
    .symbol:         _Z6n_gemmI10EStoreBf16EvPKtPKfiiiiT_.kd
    .uniform_work_group_size: 1
    .uses_dynamic_stack: false
    .vgpr_count:     68
    .vgpr_spill_count: 0
    .wavefront_size: 64
  - .agpr_count:     0
    .args:
      - .actual_access:  read_only
        .address_space:  global
        .offset:         0
        .size:           8
        .value_kind:     global_buffer
      - .actual_access:  read_only
        .address_space:  global
        .offset:         8
        .size:           8
        .value_kind:     global_buffer
      - .offset:         16
        .size:           4
        .value_kind:     by_value
      - .offset:         20
        .size:           4
        .value_kind:     by_value
      - .offset:         24
        .size:           4
        .value_kind:     by_value
      - .offset:         28
        .size:           4
        .value_kind:     by_value
      - .offset:         32
        .size:           40
        .value_kind:     by_value
    .group_segment_fixed_size: 8704
    .kernarg_segment_align: 8
    .kernarg_segment_size: 72
    .language:       OpenCL C
    .language_version:
      - 2
      - 0
    .max_flat_workgroup_size: 256
    .name:           _Z6n_gemmI7EBranchEvPKtPKfiiiiT_
    .private_segment_fixed_size: 0
    .sgpr_count:     22
    .sgpr_spill_count: 0
    .symbol:         _Z6n_gemmI7EBranchEvPKtPKfiiiiT_.kd
    .uniform_work_group_size: 1
    .uses_dynamic_stack: false
    .vgpr_count:     68
    .vgpr_spill_count: 0
    .wavefront_size: 64
  - .agpr_count:     0
    .args:
      - .actual_access:  read_only
        .address_space:  global
        .offset:         0
        .size:           8
        .value_kind:     global_buffer
      - .actual_access:  read_only
        .address_space:  global
        .offset:         8
        .size:           8
        .value_kind:     global_buffer
      - .offset:         16
        .size:           4
        .value_kind:     by_value
      - .offset:         20
        .size:           4
        .value_kind:     by_value
      - .offset:         24
        .size:           4
        .value_kind:     by_value
      - .offset:         28
        .size:           4
        .value_kind:     by_value
      - .offset:         32
        .size:           16
        .value_kind:     by_value
    .group_segment_fixed_size: 8704
    .kernarg_segment_align: 8
    .kernarg_segment_size: 48
    .language:       OpenCL C
    .language_version:
      - 2
      - 0
    .max_flat_workgroup_size: 256
    .name:           _Z6n_gemmI6EResidEvPKtPKfiiiiT_
    .private_segment_fixed_size: 0
    .sgpr_count:     22
    .sgpr_spill_count: 0
    .symbol:         _Z6n_gemmI6EResidEvPKtPKfiiiiT_.kd
    .uniform_work_group_size: 1
    .uses_dynamic_stack: false
    .vgpr_count:     68
    .vgpr_spill_count: 0
    .wavefront_size: 64
